# pool-GEMM epilogue: the four pool_scale vectors are loaded once per tile into free registers instead of 32 serialized reload/wait pairs
# speedup vs baseline: 1.0022x; 1.0022x over previous
; __device__ __forceinline__ unsigned cvtpk(float lo, float hi) { f32x2_t v = {lo, hi}; bf16x2_t b = __builtin_convertvector(v, bf16x2_t); return __builtin_bit_cast(unsigned, b); }
;     __device__ __forceinline__ void operator()(const Acc& acc, const Unit& u, int wr, int wc, int fr, int fq) const {
;         const int row0 = u.pm * BM + wr * 64 + fr, col0 = u.pn * BM + wc * 32 + 8 * fq;
; #pragma unroll
;         for (int ai = 0; ai < 2; ++ai)
; #pragma unroll
;             for (int m = 0; m < 4; ++m) { const size_t row = (size_t)(row0 + ai * HALF + m * 16);
; #pragma unroll
;                 for (int bj = 0; bj < 2; ++bj) { const int col = col0 + bj * HALF; const f32x4 s0 = *(const f32x4*)(scale + col), s1 = *(const f32x4*)(scale + col + 4);
;                     const f32x4 a = acc[ai][bj][m][0] * s0, b = acc[ai][bj][m][1] * s1;
;                     *(u32x4*)(AB + row * DM + PW + col) = (u32x4){cvtpk(a[0], a[1]), cvtpk(a[2], a[3]), cvtpk(b[0], b[1]), cvtpk(b[2], b[3])}; } }
;     }
.LBB0_889:
	v_lshl_or_b32 v140, s61, 8, v144
	v_ashrrev_i32_e32 v141, 31, v140
	v_lshl_add_u64 v[138:139], v[140:141], 2, s[14:15]
	v_mov_b64_e32 v[218:219], v[138:139]
	global_load_dwordx4 v[166:169], v[218:219], off
	global_load_dwordx4 v[170:173], v[218:219], off offset:16
	global_load_dwordx4 v[174:177], v[218:219], off offset:512
	global_load_dwordx4 v[178:181], v[218:219], off offset:528
	v_lshl_add_u32 v154, s44, 8, v142
	v_ashrrev_i32_e32 v155, 31, v154
	v_lshlrev_b64 v[156:157], 11, v[154:155]
	v_lshlrev_b64 v[158:159], 1, v[140:141]
	v_lshl_add_u64 v[140:141], s[2:3], 0, v[156:157]
	v_lshl_add_u64 v[140:141], v[140:141], 0, v[158:159]
	s_mov_b64 s[16:17], 0x40000
	s_andn2_b64 vcc, exec, s[42:43]
	s_waitcnt vmcnt(0)
	v_pk_mul_f32 v[126:127], v[126:127], v[168:169]
	v_pk_mul_f32 v[124:125], v[124:125], v[166:167]
	v_pk_mul_f32 v[146:147], v[122:123], v[172:173]
	v_pk_mul_f32 v[122:123], v[120:121], v[170:171]
	v_cvt_pk_bf16_f32 v120, v124, v125
	v_cvt_pk_bf16_f32 v121, v126, v127
	v_cvt_pk_bf16_f32 v122, v122, v123
	v_cvt_pk_bf16_f32 v123, v146, v147
	global_store_dwordx4 v[140:141], v[120:123], off offset:1024
	s_nop 1
	v_pk_mul_f32 v[118:119], v[118:119], v[176:177]
	v_pk_mul_f32 v[116:117], v[116:117], v[174:175]
	v_pk_mul_f32 v[120:121], v[114:115], v[180:181]
	v_pk_mul_f32 v[114:115], v[112:113], v[178:179]
	v_cvt_pk_bf16_f32 v112, v116, v117
	v_cvt_pk_bf16_f32 v113, v118, v119
	v_cvt_pk_bf16_f32 v114, v114, v115
	v_cvt_pk_bf16_f32 v115, v120, v121
	global_store_dwordx4 v[140:141], v[112:115], off offset:1280
	v_or_b32_e32 v120, 16, v154
	v_ashrrev_i32_e32 v121, 31, v120
	v_lshlrev_b64 v[120:121], 11, v[120:121]
	v_lshl_add_u64 v[120:121], s[2:3], 0, v[120:121]
	v_lshl_add_u64 v[120:121], v[120:121], 0, v[158:159]
	v_pk_mul_f32 v[110:111], v[110:111], v[168:169]
	v_pk_mul_f32 v[108:109], v[108:109], v[166:167]
	v_pk_mul_f32 v[112:113], v[106:107], v[172:173]
	v_pk_mul_f32 v[106:107], v[104:105], v[170:171]
	v_cvt_pk_bf16_f32 v104, v108, v109
	v_cvt_pk_bf16_f32 v105, v110, v111
	v_cvt_pk_bf16_f32 v106, v106, v107
	v_cvt_pk_bf16_f32 v107, v112, v113
	global_store_dwordx4 v[120:121], v[104:107], off offset:1024
	s_nop 1
	v_pk_mul_f32 v[102:103], v[102:103], v[176:177]
	v_pk_mul_f32 v[100:101], v[100:101], v[174:175]
	v_pk_mul_f32 v[104:105], v[98:99], v[180:181]
	v_pk_mul_f32 v[98:99], v[96:97], v[178:179]
	v_cvt_pk_bf16_f32 v96, v100, v101
	v_cvt_pk_bf16_f32 v97, v102, v103
	v_cvt_pk_bf16_f32 v98, v98, v99
	v_cvt_pk_bf16_f32 v99, v104, v105
	global_store_dwordx4 v[120:121], v[96:99], off offset:1280
	v_or_b32_e32 v104, 32, v154
	v_ashrrev_i32_e32 v105, 31, v104
	v_lshlrev_b64 v[104:105], 11, v[104:105]
	v_lshl_add_u64 v[104:105], s[2:3], 0, v[104:105]
	v_lshl_add_u64 v[104:105], v[104:105], 0, v[158:159]
	v_pk_mul_f32 v[94:95], v[94:95], v[168:169]
	v_pk_mul_f32 v[92:93], v[92:93], v[166:167]
	v_pk_mul_f32 v[96:97], v[90:91], v[172:173]
	v_pk_mul_f32 v[90:91], v[88:89], v[170:171]
	v_cvt_pk_bf16_f32 v88, v92, v93
	v_cvt_pk_bf16_f32 v89, v94, v95
	v_cvt_pk_bf16_f32 v90, v90, v91
	v_cvt_pk_bf16_f32 v91, v96, v97
	global_store_dwordx4 v[104:105], v[88:91], off offset:1024
	s_nop 1
	v_pk_mul_f32 v[86:87], v[86:87], v[176:177]
	v_pk_mul_f32 v[84:85], v[84:85], v[174:175]
	v_pk_mul_f32 v[88:89], v[82:83], v[180:181]
	v_pk_mul_f32 v[82:83], v[80:81], v[178:179]
	v_cvt_pk_bf16_f32 v80, v84, v85
	v_cvt_pk_bf16_f32 v81, v86, v87
	v_cvt_pk_bf16_f32 v82, v82, v83
	v_cvt_pk_bf16_f32 v83, v88, v89
	global_store_dwordx4 v[104:105], v[80:83], off offset:1280
	v_or_b32_e32 v88, 48, v154
	v_ashrrev_i32_e32 v89, 31, v88
	v_lshlrev_b64 v[88:89], 11, v[88:89]
	v_lshl_add_u64 v[88:89], s[2:3], 0, v[88:89]
	v_lshl_add_u64 v[88:89], v[88:89], 0, v[158:159]
	v_pk_mul_f32 v[78:79], v[78:79], v[168:169]
	v_pk_mul_f32 v[76:77], v[76:77], v[166:167]
	v_pk_mul_f32 v[80:81], v[74:75], v[172:173]
	v_pk_mul_f32 v[74:75], v[72:73], v[170:171]
	v_cvt_pk_bf16_f32 v72, v76, v77
; __device__ __forceinline__ unsigned cvtpk(float lo, float hi) { f32x2_t v = {lo, hi}; bf16x2_t b = __builtin_convertvector(v, bf16x2_t); return __builtin_bit_cast(unsigned, b); }
; #define PG8_BAR __builtin_amdgcn_s_barrier()
; template <class Epi, bool ALIGN_EPI = true>
; __device__ __forceinline__ void gemm_phase(LAS unsigned char* lds, const Gemm g, const StaticOrder& S, const Epi& E, int wave_k) {
;     ...
;         if (!has_next) break;
; #pragma unroll
;         for (int a = 0; a < 2; ++a)
; #pragma unroll
;             for (int b = 0; b < 2; ++b)
; #pragma unroll
;                 for (int m = 0; m < 4; ++m)
; #pragma unroll
;                     for (int n = 0; n < 2; ++n) acc[a][b][m][n] = (f32x4){0.f, 0.f, 0.f, 0.f};
;         cur = nxt; cA = nA; cB = nB; ++ui;
;         if constexpr (ALIGN_EPI) { if (wr == 1) PG8_BAR; }
;     __device__ __forceinline__ void operator()(const Acc& acc, const Unit& u, int wr, int wc, int fr, int fq) const {
;     ...
;             for (int m = 0; m < 4; ++m) { const size_t row = (size_t)(row0 + ai * HALF + m * 16);
; #pragma unroll
;                 for (int bj = 0; bj < 2; ++bj) { const int col = col0 + bj * HALF; const f32x4 s0 = *(const f32x4*)(scale + col), s1 = *(const f32x4*)(scale + col + 4);
;                     const f32x4 a = acc[ai][bj][m][0] * s0, b = acc[ai][bj][m][1] * s1;
;                     *(u32x4*)(AB + row * DM + PW + col) = (u32x4){cvtpk(a[0], a[1]), cvtpk(a[2], a[3]), cvtpk(b[0], b[1]), cvtpk(b[2], b[3])}; } }
;     }
	v_cvt_pk_bf16_f32 v73, v78, v79
	v_cvt_pk_bf16_f32 v74, v74, v75
	v_cvt_pk_bf16_f32 v75, v80, v81
	global_store_dwordx4 v[88:89], v[72:75], off offset:1024
	s_nop 1
	v_pk_mul_f32 v[70:71], v[70:71], v[176:177]
	v_pk_mul_f32 v[68:69], v[68:69], v[174:175]
	v_pk_mul_f32 v[72:73], v[66:67], v[180:181]
	v_pk_mul_f32 v[66:67], v[64:65], v[178:179]
	v_cvt_pk_bf16_f32 v64, v68, v69
	v_cvt_pk_bf16_f32 v65, v70, v71
	v_cvt_pk_bf16_f32 v66, v66, v67
	v_cvt_pk_bf16_f32 v67, v72, v73
	global_store_dwordx4 v[88:89], v[64:67], off offset:1280
	v_lshl_add_u64 v[72:73], v[140:141], 0, s[16:17]
	s_mov_b64 s[16:17], 0x48000
	v_pk_mul_f32 v[62:63], v[62:63], v[168:169]
	v_pk_mul_f32 v[60:61], v[60:61], v[166:167]
	v_pk_mul_f32 v[64:65], v[58:59], v[172:173]
	v_pk_mul_f32 v[58:59], v[56:57], v[170:171]
	v_cvt_pk_bf16_f32 v56, v60, v61
	v_cvt_pk_bf16_f32 v57, v62, v63
	v_cvt_pk_bf16_f32 v58, v58, v59
	v_cvt_pk_bf16_f32 v59, v64, v65
	global_store_dwordx4 v[72:73], v[56:59], off offset:1024
	s_nop 1
	v_pk_mul_f32 v[54:55], v[54:55], v[176:177]
	v_pk_mul_f32 v[52:53], v[52:53], v[174:175]
	v_pk_mul_f32 v[56:57], v[50:51], v[180:181]
	v_pk_mul_f32 v[50:51], v[48:49], v[178:179]
	v_cvt_pk_bf16_f32 v48, v52, v53
	v_cvt_pk_bf16_f32 v49, v54, v55
	v_cvt_pk_bf16_f32 v50, v50, v51
	v_cvt_pk_bf16_f32 v51, v56, v57
	global_store_dwordx4 v[72:73], v[48:51], off offset:1280
	v_lshl_add_u64 v[56:57], v[140:141], 0, s[16:17]
	s_mov_b64 s[16:17], 0x50000
	v_pk_mul_f32 v[46:47], v[46:47], v[168:169]
	v_pk_mul_f32 v[44:45], v[44:45], v[166:167]
	v_pk_mul_f32 v[48:49], v[42:43], v[172:173]
	v_pk_mul_f32 v[42:43], v[40:41], v[170:171]
	v_cvt_pk_bf16_f32 v40, v44, v45
	v_cvt_pk_bf16_f32 v41, v46, v47
	v_cvt_pk_bf16_f32 v42, v42, v43
	v_cvt_pk_bf16_f32 v43, v48, v49
	global_store_dwordx4 v[56:57], v[40:43], off offset:1024
	s_nop 1
	v_pk_mul_f32 v[38:39], v[38:39], v[176:177]
	v_pk_mul_f32 v[36:37], v[36:37], v[174:175]
	v_pk_mul_f32 v[40:41], v[34:35], v[180:181]
	v_pk_mul_f32 v[34:35], v[32:33], v[178:179]
	v_cvt_pk_bf16_f32 v32, v36, v37
	v_cvt_pk_bf16_f32 v33, v38, v39
	v_cvt_pk_bf16_f32 v34, v34, v35
	v_cvt_pk_bf16_f32 v35, v40, v41
	global_store_dwordx4 v[56:57], v[32:35], off offset:1280
	v_lshl_add_u64 v[40:41], v[140:141], 0, s[16:17]
	s_mov_b64 s[16:17], 0x58000
	v_pk_mul_f32 v[30:31], v[30:31], v[168:169]
	v_pk_mul_f32 v[28:29], v[28:29], v[166:167]
	v_pk_mul_f32 v[32:33], v[26:27], v[172:173]
	v_pk_mul_f32 v[26:27], v[24:25], v[170:171]
	v_cvt_pk_bf16_f32 v24, v28, v29
	v_cvt_pk_bf16_f32 v25, v30, v31
	v_cvt_pk_bf16_f32 v26, v26, v27
	v_cvt_pk_bf16_f32 v27, v32, v33
	global_store_dwordx4 v[40:41], v[24:27], off offset:1024
	s_nop 1
	v_pk_mul_f32 v[22:23], v[22:23], v[176:177]
	v_pk_mul_f32 v[20:21], v[20:21], v[174:175]
	v_pk_mul_f32 v[24:25], v[18:19], v[180:181]
	v_pk_mul_f32 v[18:19], v[16:17], v[178:179]
	v_cvt_pk_bf16_f32 v16, v20, v21
	v_cvt_pk_bf16_f32 v17, v22, v23
	v_cvt_pk_bf16_f32 v18, v18, v19
	v_cvt_pk_bf16_f32 v19, v24, v25
	global_store_dwordx4 v[40:41], v[16:19], off offset:1280
	v_lshl_add_u64 v[24:25], v[140:141], 0, s[16:17]
	s_mov_b64 s[16:17], -1
	v_pk_mul_f32 v[14:15], v[14:15], v[168:169]
	v_pk_mul_f32 v[12:13], v[12:13], v[166:167]
	v_pk_mul_f32 v[16:17], v[10:11], v[172:173]
	v_pk_mul_f32 v[10:11], v[8:9], v[170:171]
	v_cvt_pk_bf16_f32 v8, v12, v13
	v_cvt_pk_bf16_f32 v9, v14, v15
	v_cvt_pk_bf16_f32 v10, v10, v11
	v_cvt_pk_bf16_f32 v11, v16, v17
	global_store_dwordx4 v[24:25], v[8:11], off offset:1024
	s_nop 1
	v_pk_mul_f32 v[6:7], v[6:7], v[176:177]
	v_pk_mul_f32 v[4:5], v[4:5], v[174:175]
	v_pk_mul_f32 v[8:9], v[2:3], v[180:181]
	v_pk_mul_f32 v[2:3], v[0:1], v[178:179]
	v_cvt_pk_bf16_f32 v0, v4, v5
	v_cvt_pk_bf16_f32 v1, v6, v7
	v_cvt_pk_bf16_f32 v2, v2, v3
	v_cvt_pk_bf16_f32 v3, v8, v9
	global_store_dwordx4 v[24:25], v[0:3], off offset:1280
	s_cbranch_vccnz .LBB0_878
	s_andn2_b64 vcc, exec, s[0:1]
	s_cbranch_vccnz .LBB0_877
	s_barrier
	s_branch .LBB0_877

; #define PG8_WAIT_V(n) asm volatile("s_waitcnt vmcnt(" #n ")" ::: "memory")
; #define PG8_BAR __builtin_amdgcn_s_barrier()
; template <class Epi, bool ALIGN_EPI = true>
; __device__ __forceinline__ void gemm_phase(LAS unsigned char* lds, const Gemm g, const StaticOrder& S, const Epi& E, int wave_k) {
;     ...
;     PG8_WAIT_V(0);
;     if constexpr (!ALIGN_EPI) { if (wr == 0) PG8_BAR; }
;     PG8_BAR;
; __device__ __forceinline__ void xcd_barrier_head(const XcdBarrier& b) {
;     asm volatile("s_waitcnt vmcnt(0)" ::: "memory");
;     __syncthreads();
;     if (threadIdx.x == 0) {
;         unsigned* bar = b.bar;
;         __builtin_amdgcn_s_waitcnt(0);
;         unsigned nloc = b.st[0], nx = b.st[1];
;         if (nloc == 0u) { xcd_barrier_complete(bar, b.x, nloc, nx); b.st[0] = nloc; b.st[1] = nx; }
.LBB0_893:
	s_barrier
	s_and_saveexec_b64 s[0:1], s[88:89]
	v_readlane_b32 s54, v255, 0
	v_readlane_b32 s56, v255, 2
	v_readlane_b32 s34, v255, 4
	v_readlane_b32 s36, v255, 6
	v_readlane_b32 s40, v255, 8
	v_readlane_b32 s55, v255, 1
	v_readlane_b32 s57, v255, 3
	v_readlane_b32 s35, v255, 5
	v_readlane_b32 s37, v255, 7
	v_readlane_b32 s41, v255, 9
	s_movk_i32 s75, 0x4a0
	s_cbranch_execz .LBB0_945
	v_readlane_b32 s2, v254, 50
	s_waitcnt vmcnt(0) expcnt(0) lgkmcnt(0)
	s_nop 0
	v_mov_b32_e32 v0, s2
	ds_read_b32 v2, v0
	v_readlane_b32 s2, v254, 51
	s_waitcnt lgkmcnt(0)
	v_cmp_ne_u32_e32 vcc, 0, v2
	v_mov_b32_e32 v0, s2
	ds_read_b32 v0, v0
	s_cbranch_vccnz .LBB0_909
	s_mov_b32 s18, 1
	s_branch .LBB0_897
